# EpiRes x-out stores: nt hint removed (plain write-back stores)
# baseline (speedup 1.0000x reference)
.LBB0_619:
	s_add_i32 s20, s82, -16
	s_lshr_b32 s20, s20, 4
	s_add_i32 s20, s20, 1
	s_cmp_gt_i32 s82, 15
	s_cselect_b64 s[46:47], -1, 0
	s_and_b64 s[24:25], s[46:47], exec
	s_cselect_b32 s20, s20, 0
	s_mul_i32 s24, s20, 9
	s_add_i32 s24, s75, s24
	s_lshl_b32 s24, s24, 10
	s_ashr_i32 s25, s24, 31
	s_lshl_b64 s[24:25], s[24:25], 2
	v_lshl_or_b32 v168, s48, 8, v212
	s_add_u32 s24, s78, s24
	v_ashrrev_i32_e32 v169, 31, v168
	s_addc_u32 s25, s79, s25
	v_lshlrev_b64 v[40:41], 2, v[168:169]
	s_lshl_b32 s20, s20, 10
	v_lshl_add_u64 v[170:171], s[24:25], 0, v[40:41]
	s_lshl_b64 s[24:25], s[20:21], 2
	s_add_u32 s24, s80, s24
	s_addc_u32 s25, s81, s25
	v_lshl_add_u64 v[182:183], s[24:25], 0, v[40:41]
	global_load_dwordx4 v[40:43], v[170:171], off offset:16
	global_load_dwordx4 v[44:47], v[170:171], off
	v_mov_b32_e32 v159, v158
	global_load_dwordx4 v[52:55], v[182:183], off offset:16
	global_load_dwordx4 v[60:63], v[182:183], off
	s_and_b64 vcc, exec, s[28:29]
	s_waitcnt vmcnt(0)
	v_pk_mul_f32 v[174:175], v[158:159], v[42:43]
	v_pk_mul_f32 v[176:177], v[160:161], v[40:41]
	global_load_dwordx4 v[184:187], v[170:171], off offset:528
	global_load_dwordx4 v[40:43], v[170:171], off offset:512
	v_pk_mul_f32 v[178:179], v[158:159], v[46:47]
	v_pk_mul_f32 v[180:181], v[160:161], v[44:45]
	s_waitcnt vmcnt(1)
	v_pk_mul_f32 v[184:185], v[160:161], v[184:185]
	s_waitcnt vmcnt(0)
	v_pk_mul_f32 v[170:171], v[158:159], v[42:43]
	v_pk_mul_f32 v[172:173], v[160:161], v[40:41]
	global_load_dwordx4 v[40:43], v[182:183], off offset:528
	global_load_dwordx4 v[44:47], v[182:183], off offset:512
	v_pk_mul_f32 v[182:183], v[158:159], v[186:187]
	v_lshl_add_u32 v186, s82, 8, v210
	v_ashrrev_i32_e32 v187, 31, v186
	s_cbranch_vccz .LBB0_637
	v_lshlrev_b64 v[188:189], 10, v[186:187]
	v_lshl_add_u64 v[188:189], v[188:189], 0, v[168:169]
	v_lshlrev_b64 v[188:189], 1, v[188:189]
	v_lshl_add_u64 v[190:191], s[14:15], 0, v[188:189]
	global_load_dwordx4 v[214:217], v[190:191], off nt
	v_lshl_add_u64 v[188:189], s[26:27], 0, v[188:189]
	v_cmp_lt_i32_e32 vcc, v197, v196
	s_lshl_b32 s20, s48, 2
	s_or_b32 s24, s20, s70
	s_ashr_i32 s25, s24, 31
	s_lshl_b64 s[24:25], s[24:25], 2
	s_add_u32 s24, s76, s24
	s_addc_u32 s25, s77, s25
	s_waitcnt vmcnt(0)
	v_lshlrev_b32_e32 v192, 16, v214
	v_and_b32_e32 v193, 0xffff0000, v214
	v_lshlrev_b32_e32 v214, 16, v215
	v_and_b32_e32 v215, 0xffff0000, v215
	v_lshlrev_b32_e32 v218, 16, v216
	v_and_b32_e32 v219, 0xffff0000, v216
	v_lshlrev_b32_e32 v216, 16, v217
	v_and_b32_e32 v217, 0xffff0000, v217
	v_pk_fma_f32 v[220:221], v[142:143], v[178:179], v[214:215]
	v_pk_fma_f32 v[192:193], v[140:141], v[180:181], v[192:193]
	v_pk_fma_f32 v[222:223], v[138:139], v[174:175], v[216:217]
	v_cvt_pk_bf16_f32 v214, v192, v193
	v_pk_fma_f32 v[218:219], v[136:137], v[176:177], v[218:219]
	v_cvt_pk_bf16_f32 v215, v220, v221
	v_cvt_pk_bf16_f32 v217, v222, v223
	v_mul_f32_e32 v159, v193, v193
	v_cvt_pk_bf16_f32 v216, v218, v219
	global_store_dwordx4 v[190:191], v[214:217], off
	v_fmac_f32_e32 v159, v192, v192
	v_pk_mul_f32 v[192:193], v[60:61], v[192:193]
	v_mul_f32_e32 v214, v221, v221
	v_fmac_f32_e32 v214, v220, v220
	v_add_f32_e32 v159, v159, v214
	v_mul_f32_e32 v214, v219, v219
	v_mul_f32_e32 v215, v223, v223
	v_fmac_f32_e32 v214, v218, v218
	v_fmac_f32_e32 v215, v222, v222
	v_add_f32_e32 v214, v214, v215
	v_pk_mul_f32 v[216:217], v[62:63], v[220:221]
	v_add_f32_e32 v159, v159, v214
	v_pk_mul_f32 v[220:221], v[54:55], v[222:223]
	v_pk_mul_f32 v[218:219], v[52:53], v[218:219]
	v_cvt_pk_bf16_f32 v214, v192, v193
	v_cvt_pk_bf16_f32 v215, v216, v217
	v_cvt_pk_bf16_f32 v217, v220, v221
	s_nop 0
	v_cvt_pk_bf16_f32 v216, v218, v219
	global_store_dwordx4 v[188:189], v[214:217], off
	global_load_dwordx4 v[214:217], v[190:191], off offset:256 nt
	s_waitcnt vmcnt(0)
	v_lshlrev_b32_e32 v192, 16, v214
	v_and_b32_e32 v193, 0xffff0000, v214
	v_lshlrev_b32_e32 v214, 16, v215
	v_and_b32_e32 v215, 0xffff0000, v215
	v_lshlrev_b32_e32 v218, 16, v216
	v_and_b32_e32 v219, 0xffff0000, v216
	v_lshlrev_b32_e32 v216, 16, v217
	v_and_b32_e32 v217, 0xffff0000, v217
	v_pk_fma_f32 v[220:221], v[134:135], v[170:171], v[214:215]
	v_pk_fma_f32 v[192:193], v[132:133], v[172:173], v[192:193]
	v_pk_fma_f32 v[222:223], v[130:131], v[182:183], v[216:217]
	v_pk_fma_f32 v[218:219], v[128:129], v[184:185], v[218:219]
	v_cvt_pk_bf16_f32 v214, v192, v193
	v_cvt_pk_bf16_f32 v215, v220, v221
	v_cvt_pk_bf16_f32 v217, v222, v223
	s_nop 0
	v_cvt_pk_bf16_f32 v216, v218, v219
	global_store_dwordx4 v[190:191], v[214:217], off offset:256
	v_mul_f32_e32 v190, v193, v193
	v_mul_f32_e32 v191, v221, v221
	v_fmac_f32_e32 v190, v192, v192
	v_fmac_f32_e32 v191, v220, v220
	v_add_f32_e32 v190, v190, v191
	v_mul_f32_e32 v191, v219, v219
	v_mul_f32_e32 v214, v223, v223
	v_fmac_f32_e32 v191, v218, v218
	v_fmac_f32_e32 v214, v222, v222
	v_add_f32_e32 v191, v191, v214
	v_add_f32_e32 v190, v190, v191
	v_add_f32_e32 v224, v159, v190
	v_cndmask_b32_e32 v159, v195, v197, vcc
	v_pk_mul_f32 v[190:191], v[44:45], v[192:193]
	v_pk_mul_f32 v[192:193], v[40:41], v[218:219]
	v_lshlrev_b32_e32 v159, 2, v159
	v_pk_mul_f32 v[214:215], v[46:47], v[220:221]
	v_pk_mul_f32 v[216:217], v[42:43], v[222:223]
	v_cvt_pk_bf16_f32 v190, v190, v191
	v_cvt_pk_bf16_f32 v191, v214, v215
	v_cvt_pk_bf16_f32 v192, v192, v193
	v_cmp_lt_i32_e32 vcc, v198, v196
	v_cvt_pk_bf16_f32 v193, v216, v217
	global_store_dwordx4 v[188:189], v[190:193], off offset:256
	ds_bpermute_b32 v188, v159, v224
	v_cndmask_b32_e32 v189, v195, v198, vcc
	v_lshlrev_b32_e32 v214, 2, v189
	s_waitcnt lgkmcnt(0)
	v_add_f32_e32 v188, v224, v188
	ds_bpermute_b32 v189, v214, v188
	s_and_saveexec_b64 vcc, s[40:41]
	s_cbranch_execz .LBB0_622
	s_waitcnt lgkmcnt(0)
	v_add_f32_e32 v190, v188, v189
	v_lshlrev_b64 v[188:189], 6, v[186:187]
	v_lshl_add_u64 v[188:189], s[24:25], 0, v[188:189]
	global_store_dword v[188:189], v190, off
.LBB0_622:
	s_or_b64 exec, exec, vcc
	v_or_b32_e32 v188, 16, v186
	s_waitcnt lgkmcnt(0)
	v_ashrrev_i32_e32 v189, 31, v188
	v_lshlrev_b64 v[190:191], 10, v[188:189]
	v_lshl_add_u64 v[190:191], v[190:191], 0, v[168:169]
	v_lshlrev_b64 v[190:191], 1, v[190:191]
	v_lshl_add_u64 v[192:193], s[14:15], 0, v[190:191]
	global_load_dwordx4 v[216:219], v[192:193], off nt
	v_lshl_add_u64 v[190:191], s[26:27], 0, v[190:191]
	s_waitcnt vmcnt(0)
	v_lshlrev_b32_e32 v220, 16, v216
	v_and_b32_e32 v221, 0xffff0000, v216
	v_lshlrev_b32_e32 v216, 16, v217
	v_and_b32_e32 v217, 0xffff0000, v217
	v_lshlrev_b32_e32 v222, 16, v218
	v_and_b32_e32 v223, 0xffff0000, v218
	v_lshlrev_b32_e32 v218, 16, v219
	v_and_b32_e32 v219, 0xffff0000, v219
	v_pk_fma_f32 v[224:225], v[126:127], v[178:179], v[216:217]
	v_pk_fma_f32 v[220:221], v[124:125], v[180:181], v[220:221]
	v_pk_fma_f32 v[226:227], v[122:123], v[174:175], v[218:219]
	v_cvt_pk_bf16_f32 v216, v220, v221
	v_pk_fma_f32 v[222:223], v[120:121], v[176:177], v[222:223]
	v_cvt_pk_bf16_f32 v217, v224, v225
	v_cvt_pk_bf16_f32 v219, v226, v227
	v_mul_f32_e32 v215, v221, v221
	v_cvt_pk_bf16_f32 v218, v222, v223
	global_store_dwordx4 v[192:193], v[216:219], off
	v_fmac_f32_e32 v215, v220, v220
	s_nop 0
	v_mul_f32_e32 v216, v225, v225
	v_fmac_f32_e32 v216, v224, v224
	v_add_f32_e32 v215, v215, v216
	v_mul_f32_e32 v216, v223, v223
	v_mul_f32_e32 v217, v227, v227
	v_fmac_f32_e32 v216, v222, v222
	v_fmac_f32_e32 v217, v226, v226
	v_add_f32_e32 v216, v216, v217
	v_add_f32_e32 v215, v215, v216
	v_pk_mul_f32 v[218:219], v[62:63], v[224:225]
	v_pk_mul_f32 v[216:217], v[60:61], v[220:221]
	v_pk_mul_f32 v[220:221], v[54:55], v[226:227]
	v_pk_mul_f32 v[222:223], v[52:53], v[222:223]
	v_cvt_pk_bf16_f32 v216, v216, v217
	v_cvt_pk_bf16_f32 v217, v218, v219
	v_cvt_pk_bf16_f32 v219, v220, v221
	s_nop 0
	v_cvt_pk_bf16_f32 v218, v222, v223
	global_store_dwordx4 v[190:191], v[216:219], off
	global_load_dwordx4 v[216:219], v[192:193], off offset:256 nt
	s_waitcnt vmcnt(0)
	v_lshlrev_b32_e32 v220, 16, v216
	v_and_b32_e32 v221, 0xffff0000, v216
	v_lshlrev_b32_e32 v216, 16, v217
	v_and_b32_e32 v217, 0xffff0000, v217
	v_lshlrev_b32_e32 v222, 16, v218
	v_and_b32_e32 v223, 0xffff0000, v218
	v_lshlrev_b32_e32 v218, 16, v219
	v_and_b32_e32 v219, 0xffff0000, v219
	v_pk_fma_f32 v[224:225], v[118:119], v[170:171], v[216:217]
	v_pk_fma_f32 v[220:221], v[116:117], v[172:173], v[220:221]
	v_pk_fma_f32 v[226:227], v[114:115], v[182:183], v[218:219]
	v_pk_fma_f32 v[222:223], v[112:113], v[184:185], v[222:223]
	v_cvt_pk_bf16_f32 v216, v220, v221
	v_cvt_pk_bf16_f32 v217, v224, v225
	v_cvt_pk_bf16_f32 v219, v226, v227
	s_nop 0
	v_cvt_pk_bf16_f32 v218, v222, v223
	global_store_dwordx4 v[192:193], v[216:219], off offset:256
	v_mul_f32_e32 v192, v221, v221
	v_mul_f32_e32 v193, v225, v225
	v_fmac_f32_e32 v192, v220, v220
	v_fmac_f32_e32 v193, v224, v224
	v_add_f32_e32 v192, v192, v193
	v_mul_f32_e32 v193, v223, v223
	v_mul_f32_e32 v216, v227, v227
	v_fmac_f32_e32 v193, v222, v222
	v_fmac_f32_e32 v216, v226, v226
	v_add_f32_e32 v193, v193, v216
	v_add_f32_e32 v192, v192, v193
	v_add_f32_e32 v215, v215, v192
	v_pk_mul_f32 v[216:217], v[44:45], v[220:221]
	v_pk_mul_f32 v[218:219], v[40:41], v[222:223]
	v_pk_mul_f32 v[192:193], v[46:47], v[224:225]
	v_pk_mul_f32 v[220:221], v[42:43], v[226:227]
	v_cvt_pk_bf16_f32 v216, v216, v217
	v_cvt_pk_bf16_f32 v217, v192, v193
	v_cvt_pk_bf16_f32 v218, v218, v219
	s_nop 0
	v_cvt_pk_bf16_f32 v219, v220, v221
	global_store_dwordx4 v[190:191], v[216:219], off offset:256
	ds_bpermute_b32 v190, v159, v215
	s_waitcnt lgkmcnt(0)
	v_add_f32_e32 v190, v215, v190
	ds_bpermute_b32 v191, v214, v190
	s_and_saveexec_b64 vcc, s[40:41]
	s_cbranch_execz .LBB0_624
	v_lshlrev_b64 v[188:189], 6, v[188:189]
	s_waitcnt lgkmcnt(0)
	v_add_f32_e32 v190, v190, v191
	v_lshl_add_u64 v[188:189], s[24:25], 0, v[188:189]
	global_store_dword v[188:189], v190, off
.LBB0_624:
	s_or_b64 exec, exec, vcc
	v_or_b32_e32 v188, 32, v186
	v_ashrrev_i32_e32 v189, 31, v188
	s_waitcnt lgkmcnt(0)
	v_lshlrev_b64 v[190:191], 10, v[188:189]
	v_lshl_add_u64 v[190:191], v[190:191], 0, v[168:169]
	v_lshlrev_b64 v[190:191], 1, v[190:191]
	v_lshl_add_u64 v[192:193], s[14:15], 0, v[190:191]
	global_load_dwordx4 v[216:219], v[192:193], off nt
	v_lshl_add_u64 v[190:191], s[26:27], 0, v[190:191]
	s_waitcnt vmcnt(0)
	v_lshlrev_b32_e32 v220, 16, v216
	v_and_b32_e32 v221, 0xffff0000, v216
	v_lshlrev_b32_e32 v216, 16, v217
	v_and_b32_e32 v217, 0xffff0000, v217
	v_lshlrev_b32_e32 v222, 16, v218
	v_and_b32_e32 v223, 0xffff0000, v218
	v_lshlrev_b32_e32 v218, 16, v219
	v_and_b32_e32 v219, 0xffff0000, v219
	v_pk_fma_f32 v[224:225], v[110:111], v[178:179], v[216:217]
	v_pk_fma_f32 v[220:221], v[108:109], v[180:181], v[220:221]
	v_pk_fma_f32 v[226:227], v[106:107], v[174:175], v[218:219]
	v_cvt_pk_bf16_f32 v216, v220, v221
	v_pk_fma_f32 v[222:223], v[104:105], v[176:177], v[222:223]
	v_cvt_pk_bf16_f32 v217, v224, v225
	v_cvt_pk_bf16_f32 v219, v226, v227
	v_mul_f32_e32 v215, v221, v221
	v_cvt_pk_bf16_f32 v218, v222, v223
	global_store_dwordx4 v[192:193], v[216:219], off
	v_fmac_f32_e32 v215, v220, v220
	s_nop 0
	v_mul_f32_e32 v216, v225, v225
	v_fmac_f32_e32 v216, v224, v224
	v_add_f32_e32 v215, v215, v216
	v_mul_f32_e32 v216, v223, v223
	v_mul_f32_e32 v217, v227, v227
	v_fmac_f32_e32 v216, v222, v222
	v_fmac_f32_e32 v217, v226, v226
	v_add_f32_e32 v216, v216, v217
	v_add_f32_e32 v215, v215, v216
	v_pk_mul_f32 v[218:219], v[62:63], v[224:225]
	v_pk_mul_f32 v[216:217], v[60:61], v[220:221]
	v_pk_mul_f32 v[220:221], v[54:55], v[226:227]
	v_pk_mul_f32 v[222:223], v[52:53], v[222:223]
	v_cvt_pk_bf16_f32 v216, v216, v217
	v_cvt_pk_bf16_f32 v217, v218, v219
	v_cvt_pk_bf16_f32 v219, v220, v221
	s_nop 0
	v_cvt_pk_bf16_f32 v218, v222, v223
	global_store_dwordx4 v[190:191], v[216:219], off
	global_load_dwordx4 v[216:219], v[192:193], off offset:256 nt
	s_waitcnt vmcnt(0)
	v_lshlrev_b32_e32 v220, 16, v216
	v_and_b32_e32 v221, 0xffff0000, v216
	v_lshlrev_b32_e32 v216, 16, v217
	v_and_b32_e32 v217, 0xffff0000, v217
	v_lshlrev_b32_e32 v222, 16, v218
	v_and_b32_e32 v223, 0xffff0000, v218
	v_lshlrev_b32_e32 v218, 16, v219
	v_and_b32_e32 v219, 0xffff0000, v219
	v_pk_fma_f32 v[224:225], v[102:103], v[170:171], v[216:217]
	v_pk_fma_f32 v[220:221], v[100:101], v[172:173], v[220:221]
	v_pk_fma_f32 v[226:227], v[98:99], v[182:183], v[218:219]
	v_pk_fma_f32 v[222:223], v[96:97], v[184:185], v[222:223]
	v_cvt_pk_bf16_f32 v216, v220, v221
	v_cvt_pk_bf16_f32 v217, v224, v225
	v_cvt_pk_bf16_f32 v219, v226, v227
	s_nop 0
	v_cvt_pk_bf16_f32 v218, v222, v223
	global_store_dwordx4 v[192:193], v[216:219], off offset:256
	v_mul_f32_e32 v192, v221, v221
	v_mul_f32_e32 v193, v225, v225
	v_fmac_f32_e32 v192, v220, v220
	v_fmac_f32_e32 v193, v224, v224
	v_add_f32_e32 v192, v192, v193
	v_mul_f32_e32 v193, v223, v223
	v_mul_f32_e32 v216, v227, v227
	v_fmac_f32_e32 v193, v222, v222
	v_fmac_f32_e32 v216, v226, v226
	v_add_f32_e32 v193, v193, v216
	v_add_f32_e32 v192, v192, v193
	v_add_f32_e32 v215, v215, v192
	v_pk_mul_f32 v[216:217], v[44:45], v[220:221]
	v_pk_mul_f32 v[218:219], v[40:41], v[222:223]
	v_pk_mul_f32 v[192:193], v[46:47], v[224:225]
	v_pk_mul_f32 v[220:221], v[42:43], v[226:227]
	v_cvt_pk_bf16_f32 v216, v216, v217
	v_cvt_pk_bf16_f32 v217, v192, v193
	v_cvt_pk_bf16_f32 v218, v218, v219
	s_nop 0
	v_cvt_pk_bf16_f32 v219, v220, v221
	global_store_dwordx4 v[190:191], v[216:219], off offset:256
	ds_bpermute_b32 v190, v159, v215
	s_waitcnt lgkmcnt(0)
	v_add_f32_e32 v190, v215, v190
	ds_bpermute_b32 v191, v214, v190
	s_and_saveexec_b64 vcc, s[40:41]
	s_cbranch_execz .LBB0_626
	v_lshlrev_b64 v[188:189], 6, v[188:189]
	s_waitcnt lgkmcnt(0)
	v_add_f32_e32 v190, v190, v191
	v_lshl_add_u64 v[188:189], s[24:25], 0, v[188:189]
	global_store_dword v[188:189], v190, off
.LBB0_626:
	s_or_b64 exec, exec, vcc
	v_or_b32_e32 v188, 48, v186
	v_ashrrev_i32_e32 v189, 31, v188
	s_waitcnt lgkmcnt(0)
	v_lshlrev_b64 v[190:191], 10, v[188:189]
	v_lshl_add_u64 v[190:191], v[190:191], 0, v[168:169]
	v_lshlrev_b64 v[190:191], 1, v[190:191]
	v_lshl_add_u64 v[192:193], s[14:15], 0, v[190:191]
	global_load_dwordx4 v[216:219], v[192:193], off nt
	v_lshl_add_u64 v[190:191], s[26:27], 0, v[190:191]
	s_waitcnt vmcnt(0)
	v_lshlrev_b32_e32 v220, 16, v216
	v_and_b32_e32 v221, 0xffff0000, v216
	v_lshlrev_b32_e32 v216, 16, v217
	v_and_b32_e32 v217, 0xffff0000, v217
	v_lshlrev_b32_e32 v222, 16, v218
	v_and_b32_e32 v223, 0xffff0000, v218
	v_lshlrev_b32_e32 v218, 16, v219
	v_and_b32_e32 v219, 0xffff0000, v219
	v_pk_fma_f32 v[224:225], v[94:95], v[178:179], v[216:217]
	v_pk_fma_f32 v[220:221], v[92:93], v[180:181], v[220:221]
	v_pk_fma_f32 v[226:227], v[90:91], v[174:175], v[218:219]
	v_cvt_pk_bf16_f32 v216, v220, v221
	v_pk_fma_f32 v[222:223], v[88:89], v[176:177], v[222:223]
	v_cvt_pk_bf16_f32 v217, v224, v225
	v_cvt_pk_bf16_f32 v219, v226, v227
	v_mul_f32_e32 v215, v221, v221
	v_cvt_pk_bf16_f32 v218, v222, v223
	global_store_dwordx4 v[192:193], v[216:219], off
	v_fmac_f32_e32 v215, v220, v220
	s_nop 0
	v_mul_f32_e32 v216, v225, v225
	v_fmac_f32_e32 v216, v224, v224
	v_add_f32_e32 v215, v215, v216
	v_mul_f32_e32 v216, v223, v223
	v_mul_f32_e32 v217, v227, v227
	v_fmac_f32_e32 v216, v222, v222
	v_fmac_f32_e32 v217, v226, v226
	v_add_f32_e32 v216, v216, v217
	v_add_f32_e32 v215, v215, v216
	v_pk_mul_f32 v[218:219], v[62:63], v[224:225]
	v_pk_mul_f32 v[216:217], v[60:61], v[220:221]
	v_pk_mul_f32 v[220:221], v[54:55], v[226:227]
	v_pk_mul_f32 v[222:223], v[52:53], v[222:223]
	v_cvt_pk_bf16_f32 v216, v216, v217
	v_cvt_pk_bf16_f32 v217, v218, v219
	v_cvt_pk_bf16_f32 v219, v220, v221
	s_nop 0
	v_cvt_pk_bf16_f32 v218, v222, v223
	global_store_dwordx4 v[190:191], v[216:219], off
	global_load_dwordx4 v[216:219], v[192:193], off offset:256 nt
	s_waitcnt vmcnt(0)
	v_lshlrev_b32_e32 v220, 16, v216
	v_and_b32_e32 v221, 0xffff0000, v216
	v_lshlrev_b32_e32 v216, 16, v217
	v_and_b32_e32 v217, 0xffff0000, v217
	v_lshlrev_b32_e32 v222, 16, v218
	v_and_b32_e32 v223, 0xffff0000, v218
	v_lshlrev_b32_e32 v218, 16, v219
	v_and_b32_e32 v219, 0xffff0000, v219
	v_pk_fma_f32 v[224:225], v[86:87], v[170:171], v[216:217]
	v_pk_fma_f32 v[220:221], v[84:85], v[172:173], v[220:221]
	v_pk_fma_f32 v[226:227], v[82:83], v[182:183], v[218:219]
	v_pk_fma_f32 v[222:223], v[80:81], v[184:185], v[222:223]
	v_cvt_pk_bf16_f32 v216, v220, v221
	v_cvt_pk_bf16_f32 v217, v224, v225
	v_cvt_pk_bf16_f32 v219, v226, v227
	s_nop 0
	v_cvt_pk_bf16_f32 v218, v222, v223
	global_store_dwordx4 v[192:193], v[216:219], off offset:256
	v_mul_f32_e32 v192, v221, v221
	v_mul_f32_e32 v193, v225, v225
	v_fmac_f32_e32 v192, v220, v220
	v_fmac_f32_e32 v193, v224, v224
	v_add_f32_e32 v192, v192, v193
	v_mul_f32_e32 v193, v223, v223
	v_mul_f32_e32 v216, v227, v227
	v_fmac_f32_e32 v193, v222, v222
	v_fmac_f32_e32 v216, v226, v226
	v_add_f32_e32 v193, v193, v216
	v_add_f32_e32 v192, v192, v193
	v_add_f32_e32 v215, v215, v192
	v_pk_mul_f32 v[216:217], v[44:45], v[220:221]
	v_pk_mul_f32 v[218:219], v[40:41], v[222:223]
	v_pk_mul_f32 v[192:193], v[46:47], v[224:225]
	v_pk_mul_f32 v[220:221], v[42:43], v[226:227]
	v_cvt_pk_bf16_f32 v216, v216, v217
	v_cvt_pk_bf16_f32 v217, v192, v193
	v_cvt_pk_bf16_f32 v218, v218, v219
	s_nop 0
	v_cvt_pk_bf16_f32 v219, v220, v221
	global_store_dwordx4 v[190:191], v[216:219], off offset:256
	ds_bpermute_b32 v190, v159, v215
	s_waitcnt lgkmcnt(0)
	v_add_f32_e32 v190, v215, v190
	ds_bpermute_b32 v191, v214, v190
	s_and_saveexec_b64 vcc, s[40:41]
	s_cbranch_execz .LBB0_628
	v_lshlrev_b64 v[188:189], 6, v[188:189]
	s_waitcnt lgkmcnt(0)
	v_add_f32_e32 v190, v190, v191
	v_lshl_add_u64 v[188:189], s[24:25], 0, v[188:189]
	global_store_dword v[188:189], v190, off
.LBB0_628:
	s_or_b64 exec, exec, vcc
	v_add_u32_e32 v188, 0x80, v186
	v_ashrrev_i32_e32 v189, 31, v188
	s_waitcnt lgkmcnt(0)
	v_lshlrev_b64 v[190:191], 10, v[188:189]
	v_lshl_add_u64 v[190:191], v[190:191], 0, v[168:169]
	v_lshlrev_b64 v[190:191], 1, v[190:191]
	v_lshl_add_u64 v[192:193], s[14:15], 0, v[190:191]
	global_load_dwordx4 v[216:219], v[192:193], off nt
	v_lshl_add_u64 v[190:191], s[26:27], 0, v[190:191]
	s_waitcnt vmcnt(0)
	v_lshlrev_b32_e32 v220, 16, v216
	v_and_b32_e32 v221, 0xffff0000, v216
	v_lshlrev_b32_e32 v216, 16, v217
	v_and_b32_e32 v217, 0xffff0000, v217
	v_lshlrev_b32_e32 v222, 16, v218
	v_and_b32_e32 v223, 0xffff0000, v218
	v_lshlrev_b32_e32 v218, 16, v219
	v_and_b32_e32 v219, 0xffff0000, v219
	v_pk_fma_f32 v[224:225], v[78:79], v[178:179], v[216:217]
	v_pk_fma_f32 v[220:221], v[76:77], v[180:181], v[220:221]
	v_pk_fma_f32 v[226:227], v[74:75], v[174:175], v[218:219]
	v_cvt_pk_bf16_f32 v216, v220, v221
	v_pk_fma_f32 v[222:223], v[72:73], v[176:177], v[222:223]
	v_cvt_pk_bf16_f32 v217, v224, v225
	v_cvt_pk_bf16_f32 v219, v226, v227
	v_mul_f32_e32 v215, v221, v221
	v_cvt_pk_bf16_f32 v218, v222, v223
	global_store_dwordx4 v[192:193], v[216:219], off
	v_fmac_f32_e32 v215, v220, v220
	s_nop 0
	v_mul_f32_e32 v216, v225, v225
	v_fmac_f32_e32 v216, v224, v224
	v_add_f32_e32 v215, v215, v216
	v_mul_f32_e32 v216, v223, v223
	v_mul_f32_e32 v217, v227, v227
	v_fmac_f32_e32 v216, v222, v222
	v_fmac_f32_e32 v217, v226, v226
	v_add_f32_e32 v216, v216, v217
	v_add_f32_e32 v215, v215, v216
	v_pk_mul_f32 v[218:219], v[62:63], v[224:225]
	v_pk_mul_f32 v[216:217], v[60:61], v[220:221]
	v_pk_mul_f32 v[220:221], v[54:55], v[226:227]
	v_pk_mul_f32 v[222:223], v[52:53], v[222:223]
	v_cvt_pk_bf16_f32 v216, v216, v217
	v_cvt_pk_bf16_f32 v217, v218, v219
	v_cvt_pk_bf16_f32 v219, v220, v221
	s_nop 0
	v_cvt_pk_bf16_f32 v218, v222, v223
	global_store_dwordx4 v[190:191], v[216:219], off
	global_load_dwordx4 v[216:219], v[192:193], off offset:256 nt
	s_waitcnt vmcnt(0)
	v_lshlrev_b32_e32 v220, 16, v216
	v_and_b32_e32 v221, 0xffff0000, v216
	v_lshlrev_b32_e32 v216, 16, v217
	v_and_b32_e32 v217, 0xffff0000, v217
	v_lshlrev_b32_e32 v222, 16, v218
	v_and_b32_e32 v223, 0xffff0000, v218
	v_lshlrev_b32_e32 v218, 16, v219
	v_and_b32_e32 v219, 0xffff0000, v219
	v_pk_fma_f32 v[224:225], v[70:71], v[170:171], v[216:217]
	v_pk_fma_f32 v[220:221], v[68:69], v[172:173], v[220:221]
	v_pk_fma_f32 v[226:227], v[66:67], v[182:183], v[218:219]
	v_pk_fma_f32 v[222:223], v[64:65], v[184:185], v[222:223]
	v_cvt_pk_bf16_f32 v216, v220, v221
	v_cvt_pk_bf16_f32 v217, v224, v225
	v_cvt_pk_bf16_f32 v219, v226, v227
	s_nop 0
	v_cvt_pk_bf16_f32 v218, v222, v223
	global_store_dwordx4 v[192:193], v[216:219], off offset:256
	v_mul_f32_e32 v192, v221, v221
	v_mul_f32_e32 v193, v225, v225
	v_fmac_f32_e32 v192, v220, v220
	v_fmac_f32_e32 v193, v224, v224
	v_add_f32_e32 v192, v192, v193
	v_mul_f32_e32 v193, v223, v223
	v_mul_f32_e32 v216, v227, v227
	v_fmac_f32_e32 v193, v222, v222
	v_fmac_f32_e32 v216, v226, v226
	v_add_f32_e32 v193, v193, v216
	v_add_f32_e32 v192, v192, v193
	v_add_f32_e32 v215, v215, v192
	v_pk_mul_f32 v[216:217], v[44:45], v[220:221]
	v_pk_mul_f32 v[218:219], v[40:41], v[222:223]
	v_pk_mul_f32 v[192:193], v[46:47], v[224:225]
	v_pk_mul_f32 v[220:221], v[42:43], v[226:227]
	v_cvt_pk_bf16_f32 v216, v216, v217
	v_cvt_pk_bf16_f32 v217, v192, v193
	v_cvt_pk_bf16_f32 v218, v218, v219
	s_nop 0
	v_cvt_pk_bf16_f32 v219, v220, v221
	global_store_dwordx4 v[190:191], v[216:219], off offset:256
	ds_bpermute_b32 v190, v159, v215
	s_waitcnt lgkmcnt(0)
	v_add_f32_e32 v190, v215, v190
	ds_bpermute_b32 v191, v214, v190
	s_and_saveexec_b64 vcc, s[40:41]
	s_cbranch_execz .LBB0_630
	v_lshlrev_b64 v[188:189], 6, v[188:189]
	s_waitcnt lgkmcnt(0)
	v_add_f32_e32 v190, v190, v191
	v_lshl_add_u64 v[188:189], s[24:25], 0, v[188:189]
	global_store_dword v[188:189], v190, off
.LBB0_630:
	s_or_b64 exec, exec, vcc
	v_add_u32_e32 v188, 0x90, v186
	v_ashrrev_i32_e32 v189, 31, v188
	s_waitcnt lgkmcnt(0)
	v_lshlrev_b64 v[190:191], 10, v[188:189]
	v_lshl_add_u64 v[190:191], v[190:191], 0, v[168:169]
	v_lshlrev_b64 v[190:191], 1, v[190:191]
	v_lshl_add_u64 v[192:193], s[14:15], 0, v[190:191]
	global_load_dwordx4 v[216:219], v[192:193], off nt
	v_lshl_add_u64 v[190:191], s[26:27], 0, v[190:191]
	s_waitcnt vmcnt(0)
	v_lshlrev_b32_e32 v220, 16, v216
	v_and_b32_e32 v221, 0xffff0000, v216
	v_lshlrev_b32_e32 v216, 16, v217
	v_and_b32_e32 v217, 0xffff0000, v217
	v_lshlrev_b32_e32 v222, 16, v218
	v_and_b32_e32 v223, 0xffff0000, v218
	v_lshlrev_b32_e32 v218, 16, v219
	v_and_b32_e32 v219, 0xffff0000, v219
	v_pk_fma_f32 v[224:225], v[58:59], v[178:179], v[216:217]
	v_pk_fma_f32 v[220:221], v[56:57], v[180:181], v[220:221]
	v_pk_fma_f32 v[226:227], v[50:51], v[174:175], v[218:219]
	v_cvt_pk_bf16_f32 v216, v220, v221
	v_pk_fma_f32 v[222:223], v[48:49], v[176:177], v[222:223]
	v_cvt_pk_bf16_f32 v217, v224, v225
	v_cvt_pk_bf16_f32 v219, v226, v227
	v_mul_f32_e32 v215, v221, v221
	v_cvt_pk_bf16_f32 v218, v222, v223
	global_store_dwordx4 v[192:193], v[216:219], off
	v_fmac_f32_e32 v215, v220, v220
	s_nop 0
	v_mul_f32_e32 v216, v225, v225
	v_fmac_f32_e32 v216, v224, v224
	v_add_f32_e32 v215, v215, v216
	v_mul_f32_e32 v216, v223, v223
	v_mul_f32_e32 v217, v227, v227
	v_fmac_f32_e32 v216, v222, v222
	v_fmac_f32_e32 v217, v226, v226
	v_add_f32_e32 v216, v216, v217
	v_add_f32_e32 v215, v215, v216
	v_pk_mul_f32 v[218:219], v[62:63], v[224:225]
	v_pk_mul_f32 v[216:217], v[60:61], v[220:221]
	v_pk_mul_f32 v[220:221], v[54:55], v[226:227]
	v_pk_mul_f32 v[222:223], v[52:53], v[222:223]
	v_cvt_pk_bf16_f32 v216, v216, v217
	v_cvt_pk_bf16_f32 v217, v218, v219
	v_cvt_pk_bf16_f32 v219, v220, v221
	s_nop 0
	v_cvt_pk_bf16_f32 v218, v222, v223
	global_store_dwordx4 v[190:191], v[216:219], off
	global_load_dwordx4 v[216:219], v[192:193], off offset:256 nt
	s_waitcnt vmcnt(0)
	v_lshlrev_b32_e32 v220, 16, v216
	v_and_b32_e32 v221, 0xffff0000, v216
	v_lshlrev_b32_e32 v216, 16, v217
	v_and_b32_e32 v217, 0xffff0000, v217
	v_lshlrev_b32_e32 v222, 16, v218
	v_and_b32_e32 v223, 0xffff0000, v218
	v_lshlrev_b32_e32 v218, 16, v219
	v_and_b32_e32 v219, 0xffff0000, v219
	v_pk_fma_f32 v[224:225], v[38:39], v[170:171], v[216:217]
	v_pk_fma_f32 v[220:221], v[36:37], v[172:173], v[220:221]
	v_pk_fma_f32 v[226:227], v[34:35], v[182:183], v[218:219]
	v_pk_fma_f32 v[222:223], v[32:33], v[184:185], v[222:223]
	v_cvt_pk_bf16_f32 v216, v220, v221
	v_cvt_pk_bf16_f32 v217, v224, v225
	v_cvt_pk_bf16_f32 v219, v226, v227
	s_nop 0
	v_cvt_pk_bf16_f32 v218, v222, v223
	global_store_dwordx4 v[192:193], v[216:219], off offset:256
	v_mul_f32_e32 v192, v221, v221
	v_mul_f32_e32 v193, v225, v225
	v_fmac_f32_e32 v192, v220, v220
	v_fmac_f32_e32 v193, v224, v224
	v_add_f32_e32 v192, v192, v193
	v_mul_f32_e32 v193, v223, v223
	v_mul_f32_e32 v216, v227, v227
	v_fmac_f32_e32 v193, v222, v222
	v_fmac_f32_e32 v216, v226, v226
	v_add_f32_e32 v193, v193, v216
	v_add_f32_e32 v192, v192, v193
	v_add_f32_e32 v215, v215, v192
	v_pk_mul_f32 v[216:217], v[44:45], v[220:221]
	v_pk_mul_f32 v[218:219], v[40:41], v[222:223]
	v_pk_mul_f32 v[192:193], v[46:47], v[224:225]
	v_pk_mul_f32 v[220:221], v[42:43], v[226:227]
	v_cvt_pk_bf16_f32 v216, v216, v217
	v_cvt_pk_bf16_f32 v217, v192, v193
	v_cvt_pk_bf16_f32 v218, v218, v219
	s_nop 0
	v_cvt_pk_bf16_f32 v219, v220, v221
	global_store_dwordx4 v[190:191], v[216:219], off offset:256
	ds_bpermute_b32 v190, v159, v215
	s_waitcnt lgkmcnt(0)
	v_add_f32_e32 v190, v215, v190
	ds_bpermute_b32 v191, v214, v190
	s_and_saveexec_b64 vcc, s[40:41]
	s_cbranch_execz .LBB0_632
	v_lshlrev_b64 v[188:189], 6, v[188:189]
	s_waitcnt lgkmcnt(0)
	v_add_f32_e32 v190, v190, v191
	v_lshl_add_u64 v[188:189], s[24:25], 0, v[188:189]
	global_store_dword v[188:189], v190, off
.LBB0_632:
	s_or_b64 exec, exec, vcc
	v_add_u32_e32 v188, 0xa0, v186
	v_ashrrev_i32_e32 v189, 31, v188
	s_waitcnt lgkmcnt(0)
	v_lshlrev_b64 v[190:191], 10, v[188:189]
	v_lshl_add_u64 v[190:191], v[190:191], 0, v[168:169]
	v_lshlrev_b64 v[190:191], 1, v[190:191]
	v_lshl_add_u64 v[192:193], s[14:15], 0, v[190:191]
	global_load_dwordx4 v[216:219], v[192:193], off nt
	v_lshl_add_u64 v[190:191], s[26:27], 0, v[190:191]
	s_waitcnt vmcnt(0)
	v_lshlrev_b32_e32 v220, 16, v216
	v_and_b32_e32 v221, 0xffff0000, v216
	v_lshlrev_b32_e32 v216, 16, v217
	v_and_b32_e32 v217, 0xffff0000, v217
	v_lshlrev_b32_e32 v222, 16, v218
	v_and_b32_e32 v223, 0xffff0000, v218
	v_lshlrev_b32_e32 v218, 16, v219
	v_and_b32_e32 v219, 0xffff0000, v219
	v_pk_fma_f32 v[224:225], v[30:31], v[178:179], v[216:217]
	v_pk_fma_f32 v[220:221], v[28:29], v[180:181], v[220:221]
	v_pk_fma_f32 v[226:227], v[26:27], v[174:175], v[218:219]
	v_cvt_pk_bf16_f32 v216, v220, v221
	v_pk_fma_f32 v[222:223], v[24:25], v[176:177], v[222:223]
	v_cvt_pk_bf16_f32 v217, v224, v225
	v_cvt_pk_bf16_f32 v219, v226, v227
	v_mul_f32_e32 v215, v221, v221
	v_cvt_pk_bf16_f32 v218, v222, v223
	global_store_dwordx4 v[192:193], v[216:219], off
	v_fmac_f32_e32 v215, v220, v220
	s_nop 0
	v_mul_f32_e32 v216, v225, v225
	v_fmac_f32_e32 v216, v224, v224
	v_add_f32_e32 v215, v215, v216
	v_mul_f32_e32 v216, v223, v223
	v_mul_f32_e32 v217, v227, v227
	v_fmac_f32_e32 v216, v222, v222
	v_fmac_f32_e32 v217, v226, v226
	v_add_f32_e32 v216, v216, v217
	v_add_f32_e32 v215, v215, v216
	v_pk_mul_f32 v[218:219], v[62:63], v[224:225]
	v_pk_mul_f32 v[216:217], v[60:61], v[220:221]
	v_pk_mul_f32 v[220:221], v[54:55], v[226:227]
	v_pk_mul_f32 v[222:223], v[52:53], v[222:223]
	v_cvt_pk_bf16_f32 v216, v216, v217
	v_cvt_pk_bf16_f32 v217, v218, v219
	v_cvt_pk_bf16_f32 v219, v220, v221
	s_nop 0
	v_cvt_pk_bf16_f32 v218, v222, v223
	global_store_dwordx4 v[190:191], v[216:219], off
	global_load_dwordx4 v[216:219], v[192:193], off offset:256 nt
	s_waitcnt vmcnt(0)
	v_lshlrev_b32_e32 v220, 16, v216
	v_and_b32_e32 v221, 0xffff0000, v216
	v_lshlrev_b32_e32 v216, 16, v217
	v_and_b32_e32 v217, 0xffff0000, v217
	v_lshlrev_b32_e32 v222, 16, v218
	v_and_b32_e32 v223, 0xffff0000, v218
	v_lshlrev_b32_e32 v218, 16, v219
	v_and_b32_e32 v219, 0xffff0000, v219
	v_pk_fma_f32 v[224:225], v[22:23], v[170:171], v[216:217]
	v_pk_fma_f32 v[220:221], v[20:21], v[172:173], v[220:221]
	v_pk_fma_f32 v[226:227], v[18:19], v[182:183], v[218:219]
	v_pk_fma_f32 v[222:223], v[16:17], v[184:185], v[222:223]
	v_cvt_pk_bf16_f32 v216, v220, v221
	v_cvt_pk_bf16_f32 v217, v224, v225
	v_cvt_pk_bf16_f32 v219, v226, v227
	s_nop 0
	v_cvt_pk_bf16_f32 v218, v222, v223
	global_store_dwordx4 v[192:193], v[216:219], off offset:256
	v_mul_f32_e32 v192, v221, v221
	v_mul_f32_e32 v193, v225, v225
	v_fmac_f32_e32 v192, v220, v220
	v_fmac_f32_e32 v193, v224, v224
	v_add_f32_e32 v192, v192, v193
	v_mul_f32_e32 v193, v223, v223
	v_mul_f32_e32 v216, v227, v227
	v_fmac_f32_e32 v193, v222, v222
	v_fmac_f32_e32 v216, v226, v226
	v_add_f32_e32 v193, v193, v216
	v_add_f32_e32 v192, v192, v193
	v_add_f32_e32 v215, v215, v192
	v_pk_mul_f32 v[216:217], v[44:45], v[220:221]
	v_pk_mul_f32 v[218:219], v[40:41], v[222:223]
	v_pk_mul_f32 v[192:193], v[46:47], v[224:225]
	v_pk_mul_f32 v[220:221], v[42:43], v[226:227]
	v_cvt_pk_bf16_f32 v216, v216, v217
	v_cvt_pk_bf16_f32 v217, v192, v193
	v_cvt_pk_bf16_f32 v218, v218, v219
	s_nop 0
	v_cvt_pk_bf16_f32 v219, v220, v221
	global_store_dwordx4 v[190:191], v[216:219], off offset:256
	ds_bpermute_b32 v190, v159, v215
	s_waitcnt lgkmcnt(0)
	v_add_f32_e32 v190, v215, v190
	ds_bpermute_b32 v191, v214, v190
	s_and_saveexec_b64 vcc, s[40:41]
	s_cbranch_execz .LBB0_634
	v_lshlrev_b64 v[188:189], 6, v[188:189]
	s_waitcnt lgkmcnt(0)
	v_add_f32_e32 v190, v190, v191
	v_lshl_add_u64 v[188:189], s[24:25], 0, v[188:189]
	global_store_dword v[188:189], v190, off
.LBB0_634:
	s_or_b64 exec, exec, vcc
	v_add_u32_e32 v188, 0xb0, v186
	v_ashrrev_i32_e32 v189, 31, v188
	s_waitcnt lgkmcnt(0)
	v_lshlrev_b64 v[190:191], 10, v[188:189]
	v_lshl_add_u64 v[190:191], v[190:191], 0, v[168:169]
	v_lshlrev_b64 v[190:191], 1, v[190:191]
	v_lshl_add_u64 v[192:193], s[14:15], 0, v[190:191]
	global_load_dwordx4 v[216:219], v[192:193], off nt
	v_lshl_add_u64 v[190:191], s[26:27], 0, v[190:191]
	s_waitcnt vmcnt(0)
	v_lshlrev_b32_e32 v220, 16, v216
	v_and_b32_e32 v221, 0xffff0000, v216
	v_lshlrev_b32_e32 v216, 16, v217
	v_and_b32_e32 v217, 0xffff0000, v217
	v_lshlrev_b32_e32 v222, 16, v218
	v_and_b32_e32 v223, 0xffff0000, v218
	v_lshlrev_b32_e32 v218, 16, v219
	v_and_b32_e32 v219, 0xffff0000, v219
	v_pk_fma_f32 v[224:225], v[14:15], v[178:179], v[216:217]
	v_pk_fma_f32 v[220:221], v[12:13], v[180:181], v[220:221]
	v_pk_fma_f32 v[226:227], v[10:11], v[174:175], v[218:219]
	v_cvt_pk_bf16_f32 v216, v220, v221
	v_pk_fma_f32 v[222:223], v[8:9], v[176:177], v[222:223]
	v_cvt_pk_bf16_f32 v217, v224, v225
	v_cvt_pk_bf16_f32 v219, v226, v227
	v_mul_f32_e32 v215, v221, v221
	v_cvt_pk_bf16_f32 v218, v222, v223
	global_store_dwordx4 v[192:193], v[216:219], off
	v_fmac_f32_e32 v215, v220, v220
	s_nop 0
	v_mul_f32_e32 v216, v225, v225
	v_fmac_f32_e32 v216, v224, v224
	v_add_f32_e32 v215, v215, v216
	v_mul_f32_e32 v216, v223, v223
	v_mul_f32_e32 v217, v227, v227
	v_fmac_f32_e32 v216, v222, v222
	v_fmac_f32_e32 v217, v226, v226
	v_add_f32_e32 v216, v216, v217
	v_add_f32_e32 v215, v215, v216
	v_pk_mul_f32 v[218:219], v[62:63], v[224:225]
	v_pk_mul_f32 v[216:217], v[60:61], v[220:221]
	v_pk_mul_f32 v[220:221], v[54:55], v[226:227]
	v_pk_mul_f32 v[222:223], v[52:53], v[222:223]
	v_cvt_pk_bf16_f32 v216, v216, v217
	v_cvt_pk_bf16_f32 v217, v218, v219
	v_cvt_pk_bf16_f32 v219, v220, v221
	s_nop 0
	v_cvt_pk_bf16_f32 v218, v222, v223
	global_store_dwordx4 v[190:191], v[216:219], off
	global_load_dwordx4 v[216:219], v[192:193], off offset:256 nt
	s_waitcnt vmcnt(0)
	v_lshlrev_b32_e32 v220, 16, v216
	v_and_b32_e32 v221, 0xffff0000, v216
	v_lshlrev_b32_e32 v216, 16, v217
	v_and_b32_e32 v217, 0xffff0000, v217
	v_lshlrev_b32_e32 v222, 16, v218
	v_and_b32_e32 v223, 0xffff0000, v218
	v_lshlrev_b32_e32 v218, 16, v219
	v_and_b32_e32 v219, 0xffff0000, v219
	v_pk_fma_f32 v[224:225], v[6:7], v[170:171], v[216:217]
	v_pk_fma_f32 v[220:221], v[4:5], v[172:173], v[220:221]
	v_pk_fma_f32 v[226:227], v[2:3], v[182:183], v[218:219]
	v_pk_fma_f32 v[222:223], v[0:1], v[184:185], v[222:223]
	v_cvt_pk_bf16_f32 v216, v220, v221
	v_cvt_pk_bf16_f32 v217, v224, v225
	v_cvt_pk_bf16_f32 v219, v226, v227
	s_nop 0
	v_cvt_pk_bf16_f32 v218, v222, v223
	global_store_dwordx4 v[192:193], v[216:219], off offset:256
	v_mul_f32_e32 v192, v221, v221
	v_mul_f32_e32 v193, v225, v225
	v_fmac_f32_e32 v192, v220, v220
	v_fmac_f32_e32 v193, v224, v224
	v_add_f32_e32 v192, v192, v193
	v_mul_f32_e32 v193, v223, v223
	v_mul_f32_e32 v216, v227, v227
	v_fmac_f32_e32 v193, v222, v222
	v_fmac_f32_e32 v216, v226, v226
	v_add_f32_e32 v193, v193, v216
	v_add_f32_e32 v192, v192, v193
	v_add_f32_e32 v215, v215, v192
	ds_bpermute_b32 v159, v159, v215
	v_pk_mul_f32 v[216:217], v[44:45], v[220:221]
	v_pk_mul_f32 v[218:219], v[40:41], v[222:223]
	v_pk_mul_f32 v[192:193], v[46:47], v[224:225]
	v_pk_mul_f32 v[220:221], v[42:43], v[226:227]
	s_waitcnt lgkmcnt(0)
	v_add_f32_e32 v159, v215, v159
	v_cvt_pk_bf16_f32 v216, v216, v217
	v_cvt_pk_bf16_f32 v217, v192, v193
	v_cvt_pk_bf16_f32 v218, v218, v219
	v_cvt_pk_bf16_f32 v219, v220, v221
	global_store_dwordx4 v[190:191], v[216:219], off offset:256
	ds_bpermute_b32 v190, v214, v159
	s_and_saveexec_b64 vcc, s[40:41]
	s_cbranch_execz .LBB0_636
	v_lshlrev_b64 v[188:189], 6, v[188:189]
	s_waitcnt lgkmcnt(0)
	v_add_f32_e32 v159, v159, v190
	v_lshl_add_u64 v[188:189], s[24:25], 0, v[188:189]
	global_store_dword v[188:189], v159, off

.LBB0_642:
	s_waitcnt lgkmcnt(0)
	v_lshlrev_b64 v[190:191], 10, v[186:187]
	v_lshl_add_u64 v[190:191], v[190:191], 0, v[168:169]
	s_waitcnt vmcnt(0)
	v_lshl_add_u64 v[218:219], v[190:191], 2, v[188:189]
	v_lshlrev_b64 v[190:191], 1, v[190:191]
	v_lshl_add_u64 v[220:221], s[14:15], 0, v[190:191]
	v_lshl_add_u64 v[222:223], s[26:27], 0, v[190:191]
	global_load_dwordx4 v[190:193], v[218:219], off offset:16
	global_load_dwordx4 v[214:217], v[218:219], off
	v_cmp_lt_i32_e32 vcc, v197, v196
	s_lshl_b32 s20, s48, 2
	s_or_b32 s24, s20, s70
	s_ashr_i32 s25, s24, 31
	s_lshl_b64 s[24:25], s[24:25], 2
	s_add_u32 s24, s76, s24
	s_addc_u32 s25, s77, s25
	s_waitcnt vmcnt(1)
	v_pk_fma_f32 v[190:191], v[136:137], v[176:177], v[190:191]
	s_waitcnt vmcnt(0)
	v_pk_fma_f32 v[142:143], v[142:143], v[178:179], v[216:217]
	v_pk_fma_f32 v[140:141], v[140:141], v[180:181], v[214:215]
	v_cvt_pk_bf16_f32 v137, v142, v143
	v_pk_fma_f32 v[192:193], v[138:139], v[174:175], v[192:193]
	v_cvt_pk_bf16_f32 v136, v140, v141
	v_cvt_pk_bf16_f32 v138, v190, v191
	s_nop 0
	v_cvt_pk_bf16_f32 v139, v192, v193
	global_store_dwordx4 v[220:221], v[136:139], off
	s_nop 1
	v_mul_f32_e32 v136, v141, v141
	v_mul_f32_e32 v137, v143, v143
	v_fmac_f32_e32 v136, v140, v140
	v_fmac_f32_e32 v137, v142, v142
	v_add_f32_e32 v136, v136, v137
	v_mul_f32_e32 v137, v191, v191
	v_mul_f32_e32 v138, v193, v193
	v_fmac_f32_e32 v137, v190, v190
	v_fmac_f32_e32 v138, v192, v192
	v_add_f32_e32 v137, v137, v138
	v_add_f32_e32 v159, v136, v137
	v_pk_mul_f32 v[138:139], v[62:63], v[142:143]
	v_pk_mul_f32 v[136:137], v[60:61], v[140:141]
	v_pk_mul_f32 v[140:141], v[54:55], v[192:193]
	v_pk_mul_f32 v[142:143], v[52:53], v[190:191]
	v_cvt_pk_bf16_f32 v136, v136, v137
	v_cvt_pk_bf16_f32 v137, v138, v139
	v_cvt_pk_bf16_f32 v139, v140, v141
	s_nop 0
	v_cvt_pk_bf16_f32 v138, v142, v143
	global_store_dwordx4 v[222:223], v[136:139], off
	global_load_dwordx4 v[136:139], v[218:219], off offset:528
	s_nop 0
	global_load_dwordx4 v[140:143], v[218:219], off offset:512
	s_waitcnt vmcnt(1)
	v_pk_fma_f32 v[136:137], v[128:129], v[184:185], v[136:137]
	s_waitcnt vmcnt(0)
	v_pk_fma_f32 v[134:135], v[134:135], v[170:171], v[142:143]
	v_pk_fma_f32 v[132:133], v[132:133], v[172:173], v[140:141]
	v_cvt_pk_bf16_f32 v129, v134, v135
	v_pk_fma_f32 v[138:139], v[130:131], v[182:183], v[138:139]
	v_cvt_pk_bf16_f32 v128, v132, v133
	v_cvt_pk_bf16_f32 v130, v136, v137
	s_nop 0
	v_cvt_pk_bf16_f32 v131, v138, v139
	global_store_dwordx4 v[220:221], v[128:131], off offset:256
	s_nop 1
	v_mul_f32_e32 v128, v133, v133
	v_mul_f32_e32 v129, v135, v135
	v_fmac_f32_e32 v128, v132, v132
	v_fmac_f32_e32 v129, v134, v134
	v_add_f32_e32 v128, v128, v129
	v_mul_f32_e32 v129, v137, v137
	v_mul_f32_e32 v130, v139, v139
	v_fmac_f32_e32 v129, v136, v136
	v_fmac_f32_e32 v130, v138, v138
	v_add_f32_e32 v129, v129, v130
	v_add_f32_e32 v128, v128, v129
	v_add_f32_e32 v140, v159, v128
	v_pk_mul_f32 v[128:129], v[44:45], v[132:133]
	v_pk_mul_f32 v[130:131], v[46:47], v[134:135]
	v_cvt_pk_bf16_f32 v128, v128, v129
	v_pk_mul_f32 v[132:133], v[42:43], v[138:139]
	v_pk_mul_f32 v[134:135], v[40:41], v[136:137]
	v_cvt_pk_bf16_f32 v129, v130, v131
	v_cvt_pk_bf16_f32 v131, v132, v133
	s_nop 0
	v_cvt_pk_bf16_f32 v130, v134, v135
	global_store_dwordx4 v[222:223], v[128:131], off offset:256
	s_nop 1
	v_cndmask_b32_e32 v128, v195, v197, vcc
	v_lshlrev_b32_e32 v132, 2, v128
	ds_bpermute_b32 v128, v132, v140
	v_cmp_lt_i32_e32 vcc, v198, v196
	s_waitcnt lgkmcnt(0)
	v_add_f32_e32 v128, v140, v128
	v_cndmask_b32_e32 v129, v195, v198, vcc
	v_lshlrev_b32_e32 v133, 2, v129
	ds_bpermute_b32 v129, v133, v128
	s_and_saveexec_b64 s[46:47], s[40:41]
	s_cbranch_execz .LBB0_644
	s_waitcnt lgkmcnt(0)
	v_add_f32_e32 v130, v128, v129
	v_lshlrev_b64 v[128:129], 6, v[186:187]
	v_lshl_add_u64 v[128:129], s[24:25], 0, v[128:129]
	global_store_dword v[128:129], v130, off
.LBB0_644:
	s_or_b64 exec, exec, s[46:47]
	v_or_b32_e32 v128, 16, v186
	s_waitcnt lgkmcnt(0)
	v_ashrrev_i32_e32 v129, 31, v128
	v_lshlrev_b64 v[130:131], 10, v[128:129]
	v_lshl_add_u64 v[130:131], v[130:131], 0, v[168:169]
	v_lshl_add_u64 v[142:143], v[130:131], 2, v[188:189]
	global_load_dwordx4 v[134:137], v[142:143], off offset:16
	global_load_dwordx4 v[138:141], v[142:143], off
	v_lshlrev_b64 v[130:131], 1, v[130:131]
	v_lshl_add_u64 v[190:191], s[14:15], 0, v[130:131]
	v_lshl_add_u64 v[130:131], s[26:27], 0, v[130:131]
	s_waitcnt vmcnt(1)
	v_pk_fma_f32 v[134:135], v[120:121], v[176:177], v[134:135]
	s_waitcnt vmcnt(0)
	v_pk_fma_f32 v[126:127], v[126:127], v[178:179], v[140:141]
	v_pk_fma_f32 v[124:125], v[124:125], v[180:181], v[138:139]
	v_cvt_pk_bf16_f32 v121, v126, v127
	v_pk_fma_f32 v[136:137], v[122:123], v[174:175], v[136:137]
	v_cvt_pk_bf16_f32 v120, v124, v125
	v_cvt_pk_bf16_f32 v122, v134, v135
	s_nop 0
	v_cvt_pk_bf16_f32 v123, v136, v137
	global_store_dwordx4 v[190:191], v[120:123], off
	s_nop 1
	v_mul_f32_e32 v120, v125, v125
	v_mul_f32_e32 v121, v127, v127
	v_fmac_f32_e32 v120, v124, v124
	v_fmac_f32_e32 v121, v126, v126
	v_add_f32_e32 v120, v120, v121
	v_mul_f32_e32 v121, v135, v135
	v_mul_f32_e32 v122, v137, v137
	v_fmac_f32_e32 v121, v134, v134
	v_fmac_f32_e32 v122, v136, v136
	v_add_f32_e32 v121, v121, v122
	v_add_f32_e32 v138, v120, v121
	v_pk_mul_f32 v[122:123], v[62:63], v[126:127]
	v_pk_mul_f32 v[120:121], v[60:61], v[124:125]
	v_pk_mul_f32 v[124:125], v[54:55], v[136:137]
	v_pk_mul_f32 v[126:127], v[52:53], v[134:135]
	v_cvt_pk_bf16_f32 v120, v120, v121
	v_cvt_pk_bf16_f32 v121, v122, v123
	v_cvt_pk_bf16_f32 v123, v124, v125
	s_nop 0
	v_cvt_pk_bf16_f32 v122, v126, v127
	global_store_dwordx4 v[130:131], v[120:123], off
	global_load_dwordx4 v[120:123], v[142:143], off offset:528
	s_nop 0
	global_load_dwordx4 v[124:127], v[142:143], off offset:512
	s_waitcnt vmcnt(1)
	v_pk_fma_f32 v[120:121], v[112:113], v[184:185], v[120:121]
	s_waitcnt vmcnt(0)
	v_pk_fma_f32 v[118:119], v[118:119], v[170:171], v[126:127]
	v_pk_fma_f32 v[116:117], v[116:117], v[172:173], v[124:125]
	v_cvt_pk_bf16_f32 v113, v118, v119
	v_pk_fma_f32 v[122:123], v[114:115], v[182:183], v[122:123]
	v_cvt_pk_bf16_f32 v112, v116, v117
	v_cvt_pk_bf16_f32 v114, v120, v121
	s_nop 0
	v_cvt_pk_bf16_f32 v115, v122, v123
	global_store_dwordx4 v[190:191], v[112:115], off offset:256
	s_nop 1
	v_mul_f32_e32 v112, v117, v117
	v_mul_f32_e32 v113, v119, v119
	v_fmac_f32_e32 v112, v116, v116
	v_fmac_f32_e32 v113, v118, v118
	v_add_f32_e32 v112, v112, v113
	v_mul_f32_e32 v113, v121, v121
	v_mul_f32_e32 v114, v123, v123
	v_fmac_f32_e32 v113, v120, v120
	v_fmac_f32_e32 v114, v122, v122
	v_add_f32_e32 v113, v113, v114
	v_add_f32_e32 v112, v112, v113
	v_add_f32_e32 v124, v138, v112
	v_pk_mul_f32 v[112:113], v[44:45], v[116:117]
	v_pk_mul_f32 v[114:115], v[46:47], v[118:119]
	v_cvt_pk_bf16_f32 v112, v112, v113
	v_pk_mul_f32 v[116:117], v[42:43], v[122:123]
	v_pk_mul_f32 v[118:119], v[40:41], v[120:121]
	v_cvt_pk_bf16_f32 v113, v114, v115
	v_cvt_pk_bf16_f32 v115, v116, v117
	s_nop 0
	v_cvt_pk_bf16_f32 v114, v118, v119
	global_store_dwordx4 v[130:131], v[112:115], off offset:256
	ds_bpermute_b32 v112, v132, v124
	s_waitcnt lgkmcnt(0)
	v_add_f32_e32 v112, v124, v112
	ds_bpermute_b32 v113, v133, v112
	s_and_saveexec_b64 s[46:47], s[40:41]
	s_cbranch_execz .LBB0_646
	s_waitcnt lgkmcnt(0)
	v_add_f32_e32 v114, v112, v113
	v_lshlrev_b64 v[112:113], 6, v[128:129]
	v_lshl_add_u64 v[112:113], s[24:25], 0, v[112:113]
	global_store_dword v[112:113], v114, off
.LBB0_646:
	s_or_b64 exec, exec, s[46:47]
	v_or_b32_e32 v112, 32, v186
	s_waitcnt lgkmcnt(0)
	v_ashrrev_i32_e32 v113, 31, v112
	v_lshlrev_b64 v[114:115], 10, v[112:113]
	v_lshl_add_u64 v[114:115], v[114:115], 0, v[168:169]
	v_lshl_add_u64 v[124:125], v[114:115], 2, v[188:189]
	global_load_dwordx4 v[116:119], v[124:125], off offset:16
	global_load_dwordx4 v[120:123], v[124:125], off
	v_lshlrev_b64 v[114:115], 1, v[114:115]
	v_lshl_add_u64 v[126:127], s[14:15], 0, v[114:115]
	v_lshl_add_u64 v[114:115], s[26:27], 0, v[114:115]
	s_waitcnt vmcnt(1)
	v_pk_fma_f32 v[116:117], v[104:105], v[176:177], v[116:117]
	s_waitcnt vmcnt(0)
	v_pk_fma_f32 v[110:111], v[110:111], v[178:179], v[122:123]
	v_pk_fma_f32 v[108:109], v[108:109], v[180:181], v[120:121]
	v_cvt_pk_bf16_f32 v105, v110, v111
	v_pk_fma_f32 v[118:119], v[106:107], v[174:175], v[118:119]
	v_cvt_pk_bf16_f32 v104, v108, v109
	v_cvt_pk_bf16_f32 v106, v116, v117
	s_nop 0
	v_cvt_pk_bf16_f32 v107, v118, v119
	global_store_dwordx4 v[126:127], v[104:107], off
	s_nop 1
	v_mul_f32_e32 v104, v109, v109
	v_mul_f32_e32 v105, v111, v111
	v_fmac_f32_e32 v104, v108, v108
	v_fmac_f32_e32 v105, v110, v110
	v_add_f32_e32 v104, v104, v105
	v_mul_f32_e32 v105, v117, v117
	v_mul_f32_e32 v106, v119, v119
	v_fmac_f32_e32 v105, v116, v116
	v_fmac_f32_e32 v106, v118, v118
	v_add_f32_e32 v105, v105, v106
	v_add_f32_e32 v120, v104, v105
	v_pk_mul_f32 v[106:107], v[62:63], v[110:111]
	v_pk_mul_f32 v[104:105], v[60:61], v[108:109]
	v_pk_mul_f32 v[108:109], v[54:55], v[118:119]
	v_pk_mul_f32 v[110:111], v[52:53], v[116:117]
	v_cvt_pk_bf16_f32 v104, v104, v105
	v_cvt_pk_bf16_f32 v105, v106, v107
	v_cvt_pk_bf16_f32 v107, v108, v109
	s_nop 0
	v_cvt_pk_bf16_f32 v106, v110, v111
	global_store_dwordx4 v[114:115], v[104:107], off
	global_load_dwordx4 v[104:107], v[124:125], off offset:528
	s_nop 0
	global_load_dwordx4 v[108:111], v[124:125], off offset:512
	s_waitcnt vmcnt(1)
	v_pk_fma_f32 v[104:105], v[96:97], v[184:185], v[104:105]
	s_waitcnt vmcnt(0)
	v_pk_fma_f32 v[102:103], v[102:103], v[170:171], v[110:111]
	v_pk_fma_f32 v[100:101], v[100:101], v[172:173], v[108:109]
	v_cvt_pk_bf16_f32 v97, v102, v103
	v_pk_fma_f32 v[106:107], v[98:99], v[182:183], v[106:107]
	v_cvt_pk_bf16_f32 v96, v100, v101
	v_cvt_pk_bf16_f32 v98, v104, v105
	s_nop 0
	v_cvt_pk_bf16_f32 v99, v106, v107
	global_store_dwordx4 v[126:127], v[96:99], off offset:256
	s_nop 1
	v_mul_f32_e32 v96, v101, v101
	v_mul_f32_e32 v97, v103, v103
	v_fmac_f32_e32 v96, v100, v100
	v_fmac_f32_e32 v97, v102, v102
	v_add_f32_e32 v96, v96, v97
	v_mul_f32_e32 v97, v105, v105
	v_mul_f32_e32 v98, v107, v107
	v_fmac_f32_e32 v97, v104, v104
	v_fmac_f32_e32 v98, v106, v106
	v_add_f32_e32 v97, v97, v98
	v_add_f32_e32 v96, v96, v97
	v_add_f32_e32 v108, v120, v96
	v_pk_mul_f32 v[96:97], v[44:45], v[100:101]
	v_pk_mul_f32 v[98:99], v[46:47], v[102:103]
	v_cvt_pk_bf16_f32 v96, v96, v97
	v_pk_mul_f32 v[100:101], v[42:43], v[106:107]
	v_pk_mul_f32 v[102:103], v[40:41], v[104:105]
	v_cvt_pk_bf16_f32 v97, v98, v99
	v_cvt_pk_bf16_f32 v99, v100, v101
	s_nop 0
	v_cvt_pk_bf16_f32 v98, v102, v103
	global_store_dwordx4 v[114:115], v[96:99], off offset:256
	ds_bpermute_b32 v96, v132, v108
	s_waitcnt lgkmcnt(0)
	v_add_f32_e32 v96, v108, v96
	ds_bpermute_b32 v97, v133, v96
	s_and_saveexec_b64 s[46:47], s[40:41]
	s_cbranch_execz .LBB0_648
	s_waitcnt lgkmcnt(0)
	v_add_f32_e32 v98, v96, v97
	v_lshlrev_b64 v[96:97], 6, v[112:113]
	v_lshl_add_u64 v[96:97], s[24:25], 0, v[96:97]
	global_store_dword v[96:97], v98, off
.LBB0_648:
	s_or_b64 exec, exec, s[46:47]
	v_or_b32_e32 v96, 48, v186
	s_waitcnt lgkmcnt(0)
	v_ashrrev_i32_e32 v97, 31, v96
	v_lshlrev_b64 v[98:99], 10, v[96:97]
	v_lshl_add_u64 v[98:99], v[98:99], 0, v[168:169]
	v_lshl_add_u64 v[108:109], v[98:99], 2, v[188:189]
	global_load_dwordx4 v[100:103], v[108:109], off offset:16
	global_load_dwordx4 v[104:107], v[108:109], off
	v_lshlrev_b64 v[98:99], 1, v[98:99]
	v_lshl_add_u64 v[110:111], s[14:15], 0, v[98:99]
	v_lshl_add_u64 v[98:99], s[26:27], 0, v[98:99]
	s_waitcnt vmcnt(1)
	v_pk_fma_f32 v[100:101], v[88:89], v[176:177], v[100:101]
	s_waitcnt vmcnt(0)
	v_pk_fma_f32 v[94:95], v[94:95], v[178:179], v[106:107]
	v_pk_fma_f32 v[92:93], v[92:93], v[180:181], v[104:105]
	v_cvt_pk_bf16_f32 v89, v94, v95
	v_pk_fma_f32 v[102:103], v[90:91], v[174:175], v[102:103]
	v_cvt_pk_bf16_f32 v88, v92, v93
	v_cvt_pk_bf16_f32 v90, v100, v101
	s_nop 0
	v_cvt_pk_bf16_f32 v91, v102, v103
	global_store_dwordx4 v[110:111], v[88:91], off
	s_nop 1
	v_mul_f32_e32 v88, v93, v93
	v_mul_f32_e32 v89, v95, v95
	v_fmac_f32_e32 v88, v92, v92
	v_fmac_f32_e32 v89, v94, v94
	v_add_f32_e32 v88, v88, v89
	v_mul_f32_e32 v89, v101, v101
	v_mul_f32_e32 v90, v103, v103
	v_fmac_f32_e32 v89, v100, v100
	v_fmac_f32_e32 v90, v102, v102
	v_add_f32_e32 v89, v89, v90
	v_add_f32_e32 v104, v88, v89
	v_pk_mul_f32 v[90:91], v[62:63], v[94:95]
	v_pk_mul_f32 v[88:89], v[60:61], v[92:93]
	v_pk_mul_f32 v[92:93], v[54:55], v[102:103]
	v_pk_mul_f32 v[94:95], v[52:53], v[100:101]
	v_cvt_pk_bf16_f32 v88, v88, v89
	v_cvt_pk_bf16_f32 v89, v90, v91
	v_cvt_pk_bf16_f32 v91, v92, v93
	s_nop 0
	v_cvt_pk_bf16_f32 v90, v94, v95
	global_store_dwordx4 v[98:99], v[88:91], off
	global_load_dwordx4 v[88:91], v[108:109], off offset:528
	s_nop 0
	global_load_dwordx4 v[92:95], v[108:109], off offset:512
	s_waitcnt vmcnt(1)
	v_pk_fma_f32 v[88:89], v[80:81], v[184:185], v[88:89]
	s_waitcnt vmcnt(0)
	v_pk_fma_f32 v[86:87], v[86:87], v[170:171], v[94:95]
	v_pk_fma_f32 v[84:85], v[84:85], v[172:173], v[92:93]
	v_cvt_pk_bf16_f32 v81, v86, v87
	v_pk_fma_f32 v[90:91], v[82:83], v[182:183], v[90:91]
	v_cvt_pk_bf16_f32 v80, v84, v85
	v_cvt_pk_bf16_f32 v82, v88, v89
	s_nop 0
	v_cvt_pk_bf16_f32 v83, v90, v91
	global_store_dwordx4 v[110:111], v[80:83], off offset:256
	s_nop 1
	v_mul_f32_e32 v80, v85, v85
	v_mul_f32_e32 v81, v87, v87
	v_fmac_f32_e32 v80, v84, v84
	v_fmac_f32_e32 v81, v86, v86
	v_add_f32_e32 v80, v80, v81
	v_mul_f32_e32 v81, v89, v89
	v_mul_f32_e32 v82, v91, v91
	v_fmac_f32_e32 v81, v88, v88
	v_fmac_f32_e32 v82, v90, v90
	v_add_f32_e32 v81, v81, v82
	v_add_f32_e32 v80, v80, v81
	v_add_f32_e32 v92, v104, v80
	v_pk_mul_f32 v[80:81], v[44:45], v[84:85]
	v_pk_mul_f32 v[82:83], v[46:47], v[86:87]
	v_cvt_pk_bf16_f32 v80, v80, v81
	v_pk_mul_f32 v[84:85], v[42:43], v[90:91]
	v_pk_mul_f32 v[86:87], v[40:41], v[88:89]
	v_cvt_pk_bf16_f32 v81, v82, v83
	v_cvt_pk_bf16_f32 v83, v84, v85
	s_nop 0
	v_cvt_pk_bf16_f32 v82, v86, v87
	global_store_dwordx4 v[98:99], v[80:83], off offset:256
	ds_bpermute_b32 v80, v132, v92
	s_waitcnt lgkmcnt(0)
	v_add_f32_e32 v80, v92, v80
	ds_bpermute_b32 v81, v133, v80
	s_and_saveexec_b64 s[46:47], s[40:41]
	s_cbranch_execz .LBB0_650
	s_waitcnt lgkmcnt(0)
	v_add_f32_e32 v82, v80, v81
	v_lshlrev_b64 v[80:81], 6, v[96:97]
	v_lshl_add_u64 v[80:81], s[24:25], 0, v[80:81]
	global_store_dword v[80:81], v82, off
.LBB0_650:
	s_or_b64 exec, exec, s[46:47]
	v_add_u32_e32 v80, 0x80, v186
	s_waitcnt lgkmcnt(0)
	v_ashrrev_i32_e32 v81, 31, v80
	v_lshlrev_b64 v[82:83], 10, v[80:81]
	v_lshl_add_u64 v[82:83], v[82:83], 0, v[168:169]
	v_lshl_add_u64 v[92:93], v[82:83], 2, v[188:189]
	global_load_dwordx4 v[84:87], v[92:93], off offset:16
	global_load_dwordx4 v[88:91], v[92:93], off
	v_lshlrev_b64 v[82:83], 1, v[82:83]
	v_lshl_add_u64 v[94:95], s[14:15], 0, v[82:83]
	v_lshl_add_u64 v[82:83], s[26:27], 0, v[82:83]
	s_waitcnt vmcnt(1)
	v_pk_fma_f32 v[84:85], v[72:73], v[176:177], v[84:85]
	s_waitcnt vmcnt(0)
	v_pk_fma_f32 v[78:79], v[78:79], v[178:179], v[90:91]
	v_pk_fma_f32 v[76:77], v[76:77], v[180:181], v[88:89]
	v_cvt_pk_bf16_f32 v73, v78, v79
	v_pk_fma_f32 v[86:87], v[74:75], v[174:175], v[86:87]
	v_cvt_pk_bf16_f32 v72, v76, v77
	v_cvt_pk_bf16_f32 v74, v84, v85
	s_nop 0
	v_cvt_pk_bf16_f32 v75, v86, v87
	global_store_dwordx4 v[94:95], v[72:75], off
	s_nop 1
	v_mul_f32_e32 v72, v77, v77
	v_mul_f32_e32 v73, v79, v79
	v_fmac_f32_e32 v72, v76, v76
	v_fmac_f32_e32 v73, v78, v78
	v_add_f32_e32 v72, v72, v73
	v_mul_f32_e32 v73, v85, v85
	v_mul_f32_e32 v74, v87, v87
	v_fmac_f32_e32 v73, v84, v84
	v_fmac_f32_e32 v74, v86, v86
	v_add_f32_e32 v73, v73, v74
	v_add_f32_e32 v88, v72, v73
	v_pk_mul_f32 v[74:75], v[62:63], v[78:79]
	v_pk_mul_f32 v[72:73], v[60:61], v[76:77]
	v_pk_mul_f32 v[76:77], v[54:55], v[86:87]
	v_pk_mul_f32 v[78:79], v[52:53], v[84:85]
	v_cvt_pk_bf16_f32 v72, v72, v73
	v_cvt_pk_bf16_f32 v73, v74, v75
	v_cvt_pk_bf16_f32 v75, v76, v77
	s_nop 0
	v_cvt_pk_bf16_f32 v74, v78, v79
	global_store_dwordx4 v[82:83], v[72:75], off
	global_load_dwordx4 v[72:75], v[92:93], off offset:528
	s_nop 0
	global_load_dwordx4 v[76:79], v[92:93], off offset:512
	s_waitcnt vmcnt(1)
	v_pk_fma_f32 v[72:73], v[64:65], v[184:185], v[72:73]
	s_waitcnt vmcnt(0)
	v_pk_fma_f32 v[70:71], v[70:71], v[170:171], v[78:79]
	v_pk_fma_f32 v[68:69], v[68:69], v[172:173], v[76:77]
	v_cvt_pk_bf16_f32 v65, v70, v71
	v_pk_fma_f32 v[74:75], v[66:67], v[182:183], v[74:75]
	v_cvt_pk_bf16_f32 v64, v68, v69
	v_cvt_pk_bf16_f32 v66, v72, v73
	s_nop 0
	v_cvt_pk_bf16_f32 v67, v74, v75
	global_store_dwordx4 v[94:95], v[64:67], off offset:256
	s_nop 1
	v_mul_f32_e32 v64, v69, v69
	v_mul_f32_e32 v65, v71, v71
	v_fmac_f32_e32 v64, v68, v68
	v_fmac_f32_e32 v65, v70, v70
	v_add_f32_e32 v64, v64, v65
	v_mul_f32_e32 v65, v73, v73
	v_mul_f32_e32 v66, v75, v75
	v_fmac_f32_e32 v65, v72, v72
	v_fmac_f32_e32 v66, v74, v74
	v_add_f32_e32 v65, v65, v66
	v_add_f32_e32 v64, v64, v65
	v_add_f32_e32 v76, v88, v64
	v_pk_mul_f32 v[64:65], v[44:45], v[68:69]
	v_pk_mul_f32 v[66:67], v[46:47], v[70:71]
	v_cvt_pk_bf16_f32 v64, v64, v65
	v_pk_mul_f32 v[68:69], v[42:43], v[74:75]
	v_pk_mul_f32 v[70:71], v[40:41], v[72:73]
	v_cvt_pk_bf16_f32 v65, v66, v67
	v_cvt_pk_bf16_f32 v67, v68, v69
	s_nop 0
	v_cvt_pk_bf16_f32 v66, v70, v71
	global_store_dwordx4 v[82:83], v[64:67], off offset:256
	ds_bpermute_b32 v64, v132, v76
	s_waitcnt lgkmcnt(0)
	v_add_f32_e32 v64, v76, v64
	ds_bpermute_b32 v65, v133, v64
	s_and_saveexec_b64 s[46:47], s[40:41]
	s_cbranch_execz .LBB0_652
	s_waitcnt lgkmcnt(0)
	v_add_f32_e32 v66, v64, v65
	v_lshlrev_b64 v[64:65], 6, v[80:81]
	v_lshl_add_u64 v[64:65], s[24:25], 0, v[64:65]
	global_store_dword v[64:65], v66, off
.LBB0_652:
	s_or_b64 exec, exec, s[46:47]
	v_add_u32_e32 v64, 0x90, v186
	s_waitcnt lgkmcnt(0)
	v_ashrrev_i32_e32 v65, 31, v64
	v_lshlrev_b64 v[66:67], 10, v[64:65]
	v_lshl_add_u64 v[66:67], v[66:67], 0, v[168:169]
	v_lshl_add_u64 v[76:77], v[66:67], 2, v[188:189]
	global_load_dwordx4 v[68:71], v[76:77], off offset:16
	global_load_dwordx4 v[72:75], v[76:77], off
	v_lshlrev_b64 v[66:67], 1, v[66:67]
	v_lshl_add_u64 v[78:79], s[14:15], 0, v[66:67]
	v_lshl_add_u64 v[66:67], s[26:27], 0, v[66:67]
	s_waitcnt vmcnt(1)
	v_pk_fma_f32 v[68:69], v[48:49], v[176:177], v[68:69]
	s_waitcnt vmcnt(0)
	v_pk_fma_f32 v[58:59], v[58:59], v[178:179], v[74:75]
	v_pk_fma_f32 v[56:57], v[56:57], v[180:181], v[72:73]
	v_cvt_pk_bf16_f32 v49, v58, v59
	v_pk_fma_f32 v[70:71], v[50:51], v[174:175], v[70:71]
	v_cvt_pk_bf16_f32 v48, v56, v57
	v_cvt_pk_bf16_f32 v50, v68, v69
	s_nop 0
	v_cvt_pk_bf16_f32 v51, v70, v71
	global_store_dwordx4 v[78:79], v[48:51], off
	s_nop 1
	v_mul_f32_e32 v48, v57, v57
	v_mul_f32_e32 v49, v59, v59
	v_fmac_f32_e32 v48, v56, v56
	v_fmac_f32_e32 v49, v58, v58
	v_add_f32_e32 v48, v48, v49
	v_mul_f32_e32 v49, v69, v69
	v_mul_f32_e32 v50, v71, v71
	v_fmac_f32_e32 v49, v68, v68
	v_fmac_f32_e32 v50, v70, v70
	v_add_f32_e32 v49, v49, v50
	v_add_f32_e32 v72, v48, v49
	v_pk_mul_f32 v[50:51], v[62:63], v[58:59]
	v_pk_mul_f32 v[48:49], v[60:61], v[56:57]
	v_pk_mul_f32 v[56:57], v[54:55], v[70:71]
	v_pk_mul_f32 v[58:59], v[52:53], v[68:69]
	v_cvt_pk_bf16_f32 v48, v48, v49
	v_cvt_pk_bf16_f32 v49, v50, v51
	v_cvt_pk_bf16_f32 v51, v56, v57
	s_nop 0
	v_cvt_pk_bf16_f32 v50, v58, v59
	global_store_dwordx4 v[66:67], v[48:51], off
	global_load_dwordx4 v[48:51], v[76:77], off offset:528
	s_nop 0
	global_load_dwordx4 v[56:59], v[76:77], off offset:512
	s_waitcnt vmcnt(1)
	v_pk_fma_f32 v[48:49], v[32:33], v[184:185], v[48:49]
	s_waitcnt vmcnt(0)
	v_pk_fma_f32 v[38:39], v[38:39], v[170:171], v[58:59]
	v_pk_fma_f32 v[36:37], v[36:37], v[172:173], v[56:57]
	v_cvt_pk_bf16_f32 v33, v38, v39
	v_pk_fma_f32 v[50:51], v[34:35], v[182:183], v[50:51]
	v_cvt_pk_bf16_f32 v32, v36, v37
	v_cvt_pk_bf16_f32 v34, v48, v49
	s_nop 0
	v_cvt_pk_bf16_f32 v35, v50, v51
	global_store_dwordx4 v[78:79], v[32:35], off offset:256
	s_nop 1
	v_mul_f32_e32 v32, v37, v37
	v_mul_f32_e32 v33, v39, v39
	v_fmac_f32_e32 v32, v36, v36
	v_fmac_f32_e32 v33, v38, v38
	v_add_f32_e32 v32, v32, v33
	v_mul_f32_e32 v33, v49, v49
	v_mul_f32_e32 v34, v51, v51
	v_fmac_f32_e32 v33, v48, v48
	v_fmac_f32_e32 v34, v50, v50
	v_add_f32_e32 v33, v33, v34
	v_add_f32_e32 v32, v32, v33
	v_add_f32_e32 v56, v72, v32
	v_pk_mul_f32 v[32:33], v[44:45], v[36:37]
	v_pk_mul_f32 v[34:35], v[46:47], v[38:39]
	v_cvt_pk_bf16_f32 v32, v32, v33
	v_pk_mul_f32 v[36:37], v[42:43], v[50:51]
	v_pk_mul_f32 v[38:39], v[40:41], v[48:49]
	v_cvt_pk_bf16_f32 v33, v34, v35
	v_cvt_pk_bf16_f32 v35, v36, v37
	s_nop 0
	v_cvt_pk_bf16_f32 v34, v38, v39
	global_store_dwordx4 v[66:67], v[32:35], off offset:256
	ds_bpermute_b32 v32, v132, v56
	s_waitcnt lgkmcnt(0)
	v_add_f32_e32 v32, v56, v32
	ds_bpermute_b32 v33, v133, v32
	s_and_saveexec_b64 s[46:47], s[40:41]
	s_cbranch_execz .LBB0_654
	s_waitcnt lgkmcnt(0)
	v_add_f32_e32 v34, v32, v33
	v_lshlrev_b64 v[32:33], 6, v[64:65]
	v_lshl_add_u64 v[32:33], s[24:25], 0, v[32:33]
	global_store_dword v[32:33], v34, off
.LBB0_654:
	s_or_b64 exec, exec, s[46:47]
	v_add_u32_e32 v32, 0xa0, v186
	s_waitcnt lgkmcnt(0)
	v_ashrrev_i32_e32 v33, 31, v32
	v_lshlrev_b64 v[34:35], 10, v[32:33]
	v_lshl_add_u64 v[34:35], v[34:35], 0, v[168:169]
	v_lshl_add_u64 v[56:57], v[34:35], 2, v[188:189]
	global_load_dwordx4 v[36:39], v[56:57], off offset:16
	global_load_dwordx4 v[48:51], v[56:57], off
	v_lshlrev_b64 v[34:35], 1, v[34:35]
	v_lshl_add_u64 v[58:59], s[14:15], 0, v[34:35]
	v_lshl_add_u64 v[34:35], s[26:27], 0, v[34:35]
	s_waitcnt vmcnt(1)
	v_pk_fma_f32 v[36:37], v[24:25], v[176:177], v[36:37]
	s_waitcnt vmcnt(0)
	v_pk_fma_f32 v[30:31], v[30:31], v[178:179], v[50:51]
	v_pk_fma_f32 v[28:29], v[28:29], v[180:181], v[48:49]
	v_cvt_pk_bf16_f32 v25, v30, v31
	v_pk_fma_f32 v[38:39], v[26:27], v[174:175], v[38:39]
	v_cvt_pk_bf16_f32 v24, v28, v29
	v_cvt_pk_bf16_f32 v26, v36, v37
	s_nop 0
	v_cvt_pk_bf16_f32 v27, v38, v39
	global_store_dwordx4 v[58:59], v[24:27], off
	s_nop 1
	v_mul_f32_e32 v24, v29, v29
	v_mul_f32_e32 v25, v31, v31
	v_fmac_f32_e32 v24, v28, v28
	v_fmac_f32_e32 v25, v30, v30
	v_add_f32_e32 v24, v24, v25
	v_mul_f32_e32 v25, v37, v37
	v_mul_f32_e32 v26, v39, v39
	v_fmac_f32_e32 v25, v36, v36
	v_fmac_f32_e32 v26, v38, v38
	v_add_f32_e32 v25, v25, v26
	v_add_f32_e32 v48, v24, v25
	v_pk_mul_f32 v[26:27], v[62:63], v[30:31]
	v_pk_mul_f32 v[24:25], v[60:61], v[28:29]
	v_pk_mul_f32 v[28:29], v[54:55], v[38:39]
	v_pk_mul_f32 v[30:31], v[52:53], v[36:37]
	v_cvt_pk_bf16_f32 v24, v24, v25
	v_cvt_pk_bf16_f32 v25, v26, v27
	v_cvt_pk_bf16_f32 v27, v28, v29
	s_nop 0
	v_cvt_pk_bf16_f32 v26, v30, v31
	global_store_dwordx4 v[34:35], v[24:27], off
	global_load_dwordx4 v[24:27], v[56:57], off offset:528
	s_nop 0
	global_load_dwordx4 v[28:31], v[56:57], off offset:512
	s_waitcnt vmcnt(1)
	v_pk_fma_f32 v[24:25], v[16:17], v[184:185], v[24:25]
	s_waitcnt vmcnt(0)
	v_pk_fma_f32 v[22:23], v[22:23], v[170:171], v[30:31]
	v_pk_fma_f32 v[20:21], v[20:21], v[172:173], v[28:29]
	v_cvt_pk_bf16_f32 v17, v22, v23
	v_pk_fma_f32 v[26:27], v[18:19], v[182:183], v[26:27]
	v_cvt_pk_bf16_f32 v16, v20, v21
	v_cvt_pk_bf16_f32 v18, v24, v25
	s_nop 0
	v_cvt_pk_bf16_f32 v19, v26, v27
	global_store_dwordx4 v[58:59], v[16:19], off offset:256
	s_nop 1
	v_mul_f32_e32 v16, v21, v21
	v_mul_f32_e32 v17, v23, v23
	v_fmac_f32_e32 v16, v20, v20
	v_fmac_f32_e32 v17, v22, v22
	v_add_f32_e32 v16, v16, v17
	v_mul_f32_e32 v17, v25, v25
	v_mul_f32_e32 v18, v27, v27
	v_fmac_f32_e32 v17, v24, v24
	v_fmac_f32_e32 v18, v26, v26
	v_add_f32_e32 v17, v17, v18
	v_add_f32_e32 v16, v16, v17
	v_add_f32_e32 v28, v48, v16
	v_pk_mul_f32 v[16:17], v[44:45], v[20:21]
	v_pk_mul_f32 v[18:19], v[46:47], v[22:23]
	v_cvt_pk_bf16_f32 v16, v16, v17
	v_pk_mul_f32 v[20:21], v[42:43], v[26:27]
	v_pk_mul_f32 v[22:23], v[40:41], v[24:25]
	v_cvt_pk_bf16_f32 v17, v18, v19
	v_cvt_pk_bf16_f32 v19, v20, v21
	s_nop 0
	v_cvt_pk_bf16_f32 v18, v22, v23
	global_store_dwordx4 v[34:35], v[16:19], off offset:256
	ds_bpermute_b32 v16, v132, v28
	s_waitcnt lgkmcnt(0)
	v_add_f32_e32 v16, v28, v16
	ds_bpermute_b32 v17, v133, v16
	s_and_saveexec_b64 s[46:47], s[40:41]
	s_cbranch_execz .LBB0_656
	s_waitcnt lgkmcnt(0)
	v_add_f32_e32 v18, v16, v17
	v_lshlrev_b64 v[16:17], 6, v[32:33]
	v_lshl_add_u64 v[16:17], s[24:25], 0, v[16:17]
	global_store_dword v[16:17], v18, off
.LBB0_656:
	s_or_b64 exec, exec, s[46:47]
	v_add_u32_e32 v16, 0xb0, v186
	s_waitcnt lgkmcnt(0)
	v_ashrrev_i32_e32 v17, 31, v16
	v_lshlrev_b64 v[18:19], 10, v[16:17]
	v_lshl_add_u64 v[26:27], v[18:19], 0, v[168:169]
	v_lshl_add_u64 v[28:29], v[26:27], 2, v[188:189]
	global_load_dwordx4 v[18:21], v[28:29], off
	global_load_dwordx4 v[22:25], v[28:29], off offset:16
	v_lshlrev_b64 v[26:27], 1, v[26:27]
	v_lshl_add_u64 v[30:31], s[14:15], 0, v[26:27]
	v_lshl_add_u64 v[26:27], s[26:27], 0, v[26:27]
	s_waitcnt vmcnt(1)
	v_pk_fma_f32 v[20:21], v[14:15], v[178:179], v[20:21]
	v_pk_fma_f32 v[18:19], v[12:13], v[180:181], v[18:19]
	s_waitcnt vmcnt(0)
	v_pk_fma_f32 v[24:25], v[10:11], v[174:175], v[24:25]
	v_pk_fma_f32 v[22:23], v[8:9], v[176:177], v[22:23]
	v_cvt_pk_bf16_f32 v8, v18, v19
	v_cvt_pk_bf16_f32 v9, v20, v21
	v_cvt_pk_bf16_f32 v11, v24, v25
	v_pk_mul_f32 v[12:13], v[62:63], v[20:21]
	v_cvt_pk_bf16_f32 v10, v22, v23
	v_pk_mul_f32 v[14:15], v[60:61], v[18:19]
	v_pk_mul_f32 v[32:33], v[54:55], v[24:25]
	v_pk_mul_f32 v[34:35], v[52:53], v[22:23]
	global_store_dwordx4 v[30:31], v[8:11], off
	v_mul_f32_e32 v19, v19, v19
	v_mul_f32_e32 v21, v21, v21
	v_cvt_pk_bf16_f32 v8, v14, v15
	v_cvt_pk_bf16_f32 v9, v12, v13
	v_cvt_pk_bf16_f32 v10, v34, v35
	v_cvt_pk_bf16_f32 v11, v32, v33
	global_store_dwordx4 v[26:27], v[8:11], off
	global_load_dwordx4 v[8:11], v[28:29], off offset:512
	s_nop 0
	global_load_dwordx4 v[12:15], v[28:29], off offset:528
	v_mul_f32_e32 v23, v23, v23
	v_mul_f32_e32 v25, v25, v25
	v_fmac_f32_e32 v19, v18, v18
	v_fmac_f32_e32 v21, v20, v20
	v_fmac_f32_e32 v23, v22, v22
	v_fmac_f32_e32 v25, v24, v24
	v_add_f32_e32 v18, v19, v21
	v_add_f32_e32 v19, v23, v25
	v_add_f32_e32 v18, v18, v19
	s_waitcnt vmcnt(1)
	v_pk_fma_f32 v[6:7], v[6:7], v[170:171], v[10:11]
	v_pk_fma_f32 v[4:5], v[4:5], v[172:173], v[8:9]
	s_waitcnt vmcnt(0)
	v_pk_fma_f32 v[8:9], v[2:3], v[182:183], v[14:15]
	v_pk_fma_f32 v[10:11], v[0:1], v[184:185], v[12:13]
	v_mul_f32_e32 v12, v5, v5
	v_mul_f32_e32 v13, v7, v7
	v_mul_f32_e32 v14, v11, v11
	v_mul_f32_e32 v15, v9, v9
	v_cvt_pk_bf16_f32 v0, v4, v5
	v_cvt_pk_bf16_f32 v1, v6, v7
	v_fmac_f32_e32 v12, v4, v4
	v_fmac_f32_e32 v13, v6, v6
	v_fmac_f32_e32 v14, v10, v10
	v_fmac_f32_e32 v15, v8, v8
	v_cvt_pk_bf16_f32 v2, v10, v11
	v_cvt_pk_bf16_f32 v3, v8, v9
	global_store_dwordx4 v[30:31], v[0:3], off offset:256
	v_pk_mul_f32 v[6:7], v[46:47], v[6:7]
	v_pk_mul_f32 v[8:9], v[42:43], v[8:9]
	v_add_f32_e32 v0, v12, v13
	v_add_f32_e32 v1, v14, v15
	v_add_f32_e32 v0, v0, v1
	v_add_f32_e32 v3, v18, v0
	ds_bpermute_b32 v12, v132, v3
	v_pk_mul_f32 v[0:1], v[44:45], v[4:5]
	v_pk_mul_f32 v[4:5], v[40:41], v[10:11]
	v_cvt_pk_bf16_f32 v2, v0, v1
	s_waitcnt lgkmcnt(0)
	v_add_f32_e32 v0, v3, v12
	ds_bpermute_b32 v1, v133, v0
	v_cvt_pk_bf16_f32 v3, v6, v7
	v_cvt_pk_bf16_f32 v4, v4, v5
	v_cvt_pk_bf16_f32 v5, v8, v9
	global_store_dwordx4 v[26:27], v[2:5], off offset:256
	s_and_saveexec_b64 s[46:47], s[40:41]
	s_cbranch_execz .LBB0_658
	s_waitcnt lgkmcnt(0)
	v_add_f32_e32 v2, v0, v1
	v_lshlrev_b64 v[0:1], 6, v[16:17]
	v_lshl_add_u64 v[0:1], s[24:25], 0, v[0:1]
	global_store_dword v[0:1], v2, off
